# v043 with the whole instruction stream shifted by 4 bytes (one s_nop at entry): code placement test
# baseline (speedup 1.0000x reference)
_Z4mega6Params:
	s_nop 0
	s_mov_b32 s26, s2
	s_mov_b32 s25, 0
	v_cmp_eq_u32_e32 vcc, 0, v0
	s_and_saveexec_b64 s[2:3], vcc
	s_cbranch_execz .LBB0_3
	s_add_i32 s6, 0, 0x20000
	v_mov_b32_e32 v1, 0
	v_mov_b32_e32 v2, s6
	s_add_i32 s6, 0, 0x20004
	s_mov_b64 s[4:5], exec
	ds_write_b32 v2, v1
	v_mov_b32_e32 v2, s6
	ds_write_b32 v2, v1
	v_mbcnt_lo_u32_b32 v1, s4, 0
	v_mbcnt_hi_u32_b32 v1, s5, v1
	v_cmp_eq_u32_e32 vcc, 0, v1
	s_getreg_b32 s6, hwreg(HW_REG_XCC_ID, 0, 4)
	s_and_b64 s[8:9], exec, vcc
	s_mov_b64 exec, s[8:9]
	s_cbranch_execz .LBB0_3
	s_load_dwordx2 s[8:9], s[0:1], 0xf8
	s_lshl_b32 s6, s6, 8
	s_and_b32 s6, s6, 0xf00
	s_bcnt1_i32_b64 s4, s[4:5]
	v_mov_b32_e32 v1, s6
	v_mov_b32_e32 v2, s4
	s_waitcnt lgkmcnt(0)
	global_atomic_add v1, v2, s[8:9] offset:1024
